# out-proj and PLE GEMM instances: last tile of each workgroup also stored write-through (sc1)
# speedup vs baseline: 1.0092x; 1.0028x over previous
.LBB0_82:
	s_add_u32 s31, s16, s30
	s_addc_u32 s41, s17, 0
	s_add_u32 s36, s31, 0x100
	s_addc_u32 s37, s41, 0
	s_and_b64 s[34:35], s[28:29], exec
	s_cselect_b32 s37, s21, s37
	s_cselect_b32 s36, s76, s36
	s_add_u32 s30, s14, s30
	s_addc_u32 s34, s15, 0
	s_add_u32 s30, s30, 0x100
	s_addc_u32 s34, s34, 0
	s_add_i32 s92, 0, 0x10000
	s_and_b64 s[28:29], s[28:29], exec
	s_cselect_b32 s39, s19, s34
	s_cselect_b32 s38, s77, s30
	s_add_u32 s40, s31, 0x10080
	s_addc_u32 s41, s41, 0
	s_add_i32 s64, s92, s53
	s_add_i32 m0, s13, 0xc000
	s_add_i32 s93, s13, 0xe000
	s_add_i32 s97, 0, 0x14000
	s_add_i32 s70, s64, 0x2000
	s_add_u32 s34, s38, 0x10000
	v_add_u32_e32 v147, s92, v137
	s_addc_u32 s35, s39, 0
	s_add_i32 s96, s97, s53
	ds_read_b128 v[148:151], v147
	ds_read_b128 v[152:155], v147 offset:1024
	ds_read_b128 v[156:159], v147 offset:2048
	ds_read_b128 v[176:179], v147 offset:3072
	s_add_i32 s51, s96, 0x2000
	s_add_i32 s95, 0, 0x18000
	s_add_u32 s30, s36, 0x10000
	s_addc_u32 s31, s37, 0
	s_add_i32 s94, s95, s53
	s_add_i32 s91, 0, 0x1c000
	s_add_i32 s59, s94, 0x2000
	s_add_u32 s28, s38, 0x10080
	s_addc_u32 s29, s39, 0
	s_add_i32 vcc_hi, s91, s53
	s_add_i32 vcc_lo, vcc_hi, 0x2000
	v_lshl_add_u64 v[214:215], s[40:41], 0, v[130:131]
	ds_read_b128 v[180:183], v146
	ds_read_b128 v[184:187], v146 offset:1024
	ds_read_b128 v[188:191], v146 offset:2048
	ds_read_b128 v[192:195], v146 offset:3072
	ds_read_b128 v[196:199], v146 offset:4096
	ds_read_b128 v[200:203], v146 offset:5120
	ds_read_b128 v[206:209], v146 offset:6144
	ds_read_b128 v[210:213], v146 offset:7168
	global_load_lds_dwordx4 v[214:215], off
	v_lshl_add_u64 v[214:215], s[40:41], 0, v[132:133]
	s_mov_b32 m0, s93
	s_nop 0
	global_load_lds_dwordx4 v[214:215], off
	s_waitcnt lgkmcnt(8)
	s_barrier
	s_waitcnt lgkmcnt(0)
	s_setprio 1
	s_waitcnt lgkmcnt(0)
	v_mfma_f32_16x16x32_bf16 v[126:129], v[148:151], v[180:183], v[126:129]
	v_mfma_f32_16x16x32_bf16 v[122:125], v[156:159], v[180:183], v[122:125]
	v_mfma_f32_16x16x32_bf16 v[118:121], v[148:151], v[188:191], v[118:121]
	v_mfma_f32_16x16x32_bf16 v[114:117], v[156:159], v[188:191], v[114:117]
	v_mfma_f32_16x16x32_bf16 v[102:105], v[148:151], v[196:199], v[102:105]
	v_mfma_f32_16x16x32_bf16 v[98:101], v[156:159], v[196:199], v[98:101]
	v_mfma_f32_16x16x32_bf16 v[86:89], v[148:151], v[206:209], v[86:89]
	v_mfma_f32_16x16x32_bf16 v[82:85], v[156:159], v[206:209], v[82:85]
	v_mfma_f32_16x16x32_bf16 v[126:129], v[152:155], v[184:187], v[126:129]
	v_mfma_f32_16x16x32_bf16 v[122:125], v[176:179], v[184:187], v[122:125]
	v_mfma_f32_16x16x32_bf16 v[118:121], v[152:155], v[192:195], v[118:121]
	v_mfma_f32_16x16x32_bf16 v[114:117], v[176:179], v[192:195], v[114:117]
	v_mfma_f32_16x16x32_bf16 v[102:105], v[152:155], v[200:203], v[102:105]
	v_mfma_f32_16x16x32_bf16 v[98:101], v[176:179], v[200:203], v[98:101]
	v_mfma_f32_16x16x32_bf16 v[86:89], v[152:155], v[210:213], v[86:89]
	v_mfma_f32_16x16x32_bf16 v[82:85], v[176:179], v[210:213], v[82:85]
	s_setprio 0
	s_barrier
	s_mov_b32 m0, s64
	v_add_u32_e32 v147, s97, v137
	v_lshl_add_u64 v[230:231], s[38:39], 0, v[0:1]
	ds_read_b128 v[214:217], v147
	ds_read_b128 v[218:221], v147 offset:1024
	ds_read_b128 v[222:225], v147 offset:2048
	ds_read_b128 v[226:229], v147 offset:3072
	global_load_lds_dwordx4 v[230:231], off
	v_lshl_add_u64 v[232:233], s[38:39], 0, v[134:135]
	s_mov_b32 m0, s70
	s_nop 0
	global_load_lds_dwordx4 v[232:233], off
	s_barrier
	s_waitcnt lgkmcnt(0)
	s_setprio 1
	s_waitcnt lgkmcnt(0)
	v_mfma_f32_16x16x32_bf16 v[110:113], v[214:217], v[180:183], v[110:113]
	v_mfma_f32_16x16x32_bf16 v[106:109], v[222:225], v[180:183], v[106:109]
	v_mfma_f32_16x16x32_bf16 v[94:97], v[214:217], v[188:191], v[94:97]
	v_mfma_f32_16x16x32_bf16 v[90:93], v[222:225], v[188:191], v[90:93]
	v_mfma_f32_16x16x32_bf16 v[78:81], v[214:217], v[196:199], v[78:81]
	v_mfma_f32_16x16x32_bf16 v[74:77], v[222:225], v[196:199], v[74:77]
	v_mfma_f32_16x16x32_bf16 v[70:73], v[214:217], v[206:209], v[70:73]
	v_mfma_f32_16x16x32_bf16 v[66:69], v[222:225], v[206:209], v[66:69]
	v_mfma_f32_16x16x32_bf16 v[110:113], v[218:221], v[184:187], v[110:113]
	v_mfma_f32_16x16x32_bf16 v[106:109], v[226:229], v[184:187], v[106:109]
	v_mfma_f32_16x16x32_bf16 v[94:97], v[218:221], v[192:195], v[94:97]
	v_mfma_f32_16x16x32_bf16 v[90:93], v[226:229], v[192:195], v[90:93]
	v_mfma_f32_16x16x32_bf16 v[78:81], v[218:221], v[200:203], v[78:81]
	v_mfma_f32_16x16x32_bf16 v[74:77], v[226:229], v[200:203], v[74:77]
	v_mfma_f32_16x16x32_bf16 v[70:73], v[218:221], v[210:213], v[70:73]
	v_mfma_f32_16x16x32_bf16 v[66:69], v[226:229], v[210:213], v[66:69]
	s_setprio 0
	s_mov_b32 m0, s13
	v_lshl_add_u64 v[234:235], s[36:37], 0, v[130:131]
	s_barrier
	ds_read_b128 v[180:183], v146 offset:16384
	ds_read_b128 v[184:187], v146 offset:17408
	ds_read_b128 v[188:191], v146 offset:18432
	ds_read_b128 v[192:195], v146 offset:19456
	ds_read_b128 v[196:199], v146 offset:20480
	ds_read_b128 v[200:203], v146 offset:21504
	ds_read_b128 v[206:209], v146 offset:22528
	ds_read_b128 v[210:213], v146 offset:23552
	global_load_lds_dwordx4 v[234:235], off
	v_lshl_add_u64 v[236:237], s[36:37], 0, v[132:133]
	s_mov_b32 m0, s54
	s_nop 0
	global_load_lds_dwordx4 v[236:237], off
	s_barrier
	s_waitcnt lgkmcnt(0)
	s_setprio 1
	s_waitcnt lgkmcnt(0)
	v_mfma_f32_16x16x32_bf16 v[62:65], v[148:151], v[180:183], v[62:65]
	v_mfma_f32_16x16x32_bf16 v[58:61], v[156:159], v[180:183], v[58:61]
	v_mfma_f32_16x16x32_bf16 v[54:57], v[148:151], v[188:191], v[54:57]
	v_mfma_f32_16x16x32_bf16 v[50:53], v[156:159], v[188:191], v[50:53]
	v_mfma_f32_16x16x32_bf16 v[38:41], v[148:151], v[196:199], v[38:41]
	v_mfma_f32_16x16x32_bf16 v[34:37], v[156:159], v[196:199], v[34:37]
	v_mfma_f32_16x16x32_bf16 v[22:25], v[148:151], v[206:209], v[22:25]
	v_mfma_f32_16x16x32_bf16 v[18:21], v[156:159], v[206:209], v[18:21]
	v_mfma_f32_16x16x32_bf16 v[62:65], v[152:155], v[184:187], v[62:65]
	v_mfma_f32_16x16x32_bf16 v[58:61], v[176:179], v[184:187], v[58:61]
	v_mfma_f32_16x16x32_bf16 v[54:57], v[152:155], v[192:195], v[54:57]
	v_mfma_f32_16x16x32_bf16 v[50:53], v[176:179], v[192:195], v[50:53]
	v_mfma_f32_16x16x32_bf16 v[38:41], v[152:155], v[200:203], v[38:41]
	v_mfma_f32_16x16x32_bf16 v[34:37], v[176:179], v[200:203], v[34:37]
	v_mfma_f32_16x16x32_bf16 v[22:25], v[152:155], v[210:213], v[22:25]
	v_mfma_f32_16x16x32_bf16 v[18:21], v[176:179], v[210:213], v[18:21]
	s_setprio 0
	s_barrier
	s_mov_b32 m0, s96
	v_lshl_add_u64 v[148:149], s[34:35], 0, v[0:1]
	global_load_lds_dwordx4 v[148:149], off
	v_lshl_add_u64 v[148:149], s[34:35], 0, v[134:135]
	s_mov_b32 m0, s51
	s_nop 0
	global_load_lds_dwordx4 v[148:149], off
	s_waitcnt vmcnt(6)
	s_barrier
	s_setprio 1
	v_mfma_f32_16x16x32_bf16 v[46:49], v[214:217], v[180:183], v[46:49]
	v_mfma_f32_16x16x32_bf16 v[42:45], v[222:225], v[180:183], v[42:45]
	v_mfma_f32_16x16x32_bf16 v[30:33], v[214:217], v[188:191], v[30:33]
	v_mfma_f32_16x16x32_bf16 v[26:29], v[222:225], v[188:191], v[26:29]
	v_mfma_f32_16x16x32_bf16 v[14:17], v[214:217], v[196:199], v[14:17]
	v_mfma_f32_16x16x32_bf16 v[10:13], v[222:225], v[196:199], v[10:13]
	v_mfma_f32_16x16x32_bf16 v[6:9], v[214:217], v[206:209], v[6:9]
	v_mfma_f32_16x16x32_bf16 v[2:5], v[222:225], v[206:209], v[2:5]
	v_mfma_f32_16x16x32_bf16 v[46:49], v[218:221], v[184:187], v[46:49]
	v_mfma_f32_16x16x32_bf16 v[42:45], v[226:229], v[184:187], v[42:45]
	v_mfma_f32_16x16x32_bf16 v[30:33], v[218:221], v[192:195], v[30:33]
	v_mfma_f32_16x16x32_bf16 v[26:29], v[226:229], v[192:195], v[26:29]
	v_mfma_f32_16x16x32_bf16 v[14:17], v[218:221], v[200:203], v[14:17]
	v_mfma_f32_16x16x32_bf16 v[10:13], v[226:229], v[200:203], v[10:13]
	v_mfma_f32_16x16x32_bf16 v[6:9], v[218:221], v[210:213], v[6:9]
	v_mfma_f32_16x16x32_bf16 v[2:5], v[226:229], v[210:213], v[2:5]
	s_setprio 0
	v_add_u32_e32 v147, s95, v137
	s_barrier
	ds_read_b128 v[148:151], v147
	ds_read_b128 v[152:155], v147 offset:1024
	ds_read_b128 v[156:159], v147 offset:2048
	ds_read_b128 v[176:179], v147 offset:3072
	s_mov_b32 m0, s55
	v_lshl_add_u64 v[214:215], s[30:31], 0, v[130:131]
	ds_read_b128 v[180:183], v146 offset:32768
	ds_read_b128 v[184:187], v146 offset:33792
	ds_read_b128 v[188:191], v146 offset:34816
	ds_read_b128 v[192:195], v146 offset:35840
	ds_read_b128 v[196:199], v146 offset:36864
	ds_read_b128 v[200:203], v146 offset:37888
	ds_read_b128 v[206:209], v146 offset:38912
	ds_read_b128 v[210:213], v146 offset:39936
	global_load_lds_dwordx4 v[214:215], off
	v_lshl_add_u64 v[214:215], s[30:31], 0, v[132:133]
	s_mov_b32 m0, s60
	s_nop 0
	global_load_lds_dwordx4 v[214:215], off
	s_waitcnt lgkmcnt(8)
	s_barrier
	s_waitcnt lgkmcnt(0)
	s_setprio 1
	s_waitcnt lgkmcnt(0)
	v_mfma_f32_16x16x32_bf16 v[126:129], v[148:151], v[180:183], v[126:129]
	v_mfma_f32_16x16x32_bf16 v[122:125], v[156:159], v[180:183], v[122:125]
	v_mfma_f32_16x16x32_bf16 v[118:121], v[148:151], v[188:191], v[118:121]
	v_mfma_f32_16x16x32_bf16 v[114:117], v[156:159], v[188:191], v[114:117]
	v_mfma_f32_16x16x32_bf16 v[102:105], v[148:151], v[196:199], v[102:105]
	v_mfma_f32_16x16x32_bf16 v[98:101], v[156:159], v[196:199], v[98:101]
	v_mfma_f32_16x16x32_bf16 v[86:89], v[148:151], v[206:209], v[86:89]
	v_mfma_f32_16x16x32_bf16 v[82:85], v[156:159], v[206:209], v[82:85]
	v_mfma_f32_16x16x32_bf16 v[126:129], v[152:155], v[184:187], v[126:129]
	v_mfma_f32_16x16x32_bf16 v[122:125], v[176:179], v[184:187], v[122:125]
	v_mfma_f32_16x16x32_bf16 v[118:121], v[152:155], v[192:195], v[118:121]
	v_mfma_f32_16x16x32_bf16 v[114:117], v[176:179], v[192:195], v[114:117]
	v_mfma_f32_16x16x32_bf16 v[102:105], v[152:155], v[200:203], v[102:105]
	v_mfma_f32_16x16x32_bf16 v[98:101], v[176:179], v[200:203], v[98:101]
	v_mfma_f32_16x16x32_bf16 v[86:89], v[152:155], v[210:213], v[86:89]
	v_mfma_f32_16x16x32_bf16 v[82:85], v[176:179], v[210:213], v[82:85]
	s_setprio 0
	s_barrier
	s_mov_b32 m0, s94
	v_add_u32_e32 v147, s91, v137
	v_lshl_add_u64 v[230:231], v[230:231], 0, s[88:89]
	ds_read_b128 v[214:217], v147
	ds_read_b128 v[218:221], v147 offset:1024
	ds_read_b128 v[222:225], v147 offset:2048
	ds_read_b128 v[226:229], v147 offset:3072
	global_load_lds_dwordx4 v[230:231], off
	v_lshl_add_u64 v[230:231], v[232:233], 0, s[88:89]
	s_mov_b32 m0, s59
	s_nop 0
	global_load_lds_dwordx4 v[230:231], off
	s_barrier
	s_waitcnt lgkmcnt(0)
	s_setprio 1
	s_waitcnt lgkmcnt(0)
	v_mfma_f32_16x16x32_bf16 v[110:113], v[214:217], v[180:183], v[110:113]
	v_mfma_f32_16x16x32_bf16 v[106:109], v[222:225], v[180:183], v[106:109]
	v_mfma_f32_16x16x32_bf16 v[94:97], v[214:217], v[188:191], v[94:97]
	v_mfma_f32_16x16x32_bf16 v[90:93], v[222:225], v[188:191], v[90:93]
	v_mfma_f32_16x16x32_bf16 v[78:81], v[214:217], v[196:199], v[78:81]
	v_mfma_f32_16x16x32_bf16 v[74:77], v[222:225], v[196:199], v[74:77]
	v_mfma_f32_16x16x32_bf16 v[70:73], v[214:217], v[206:209], v[70:73]
	v_mfma_f32_16x16x32_bf16 v[66:69], v[222:225], v[206:209], v[66:69]
	v_mfma_f32_16x16x32_bf16 v[110:113], v[218:221], v[184:187], v[110:113]
	v_mfma_f32_16x16x32_bf16 v[106:109], v[226:229], v[184:187], v[106:109]
	v_mfma_f32_16x16x32_bf16 v[94:97], v[218:221], v[192:195], v[94:97]
	v_mfma_f32_16x16x32_bf16 v[90:93], v[226:229], v[192:195], v[90:93]
	v_mfma_f32_16x16x32_bf16 v[78:81], v[218:221], v[200:203], v[78:81]
	v_mfma_f32_16x16x32_bf16 v[74:77], v[226:229], v[200:203], v[74:77]
	v_mfma_f32_16x16x32_bf16 v[70:73], v[218:221], v[210:213], v[70:73]
	v_mfma_f32_16x16x32_bf16 v[66:69], v[226:229], v[210:213], v[66:69]
	s_setprio 0
	s_mov_b32 m0, s61
	v_lshl_add_u64 v[230:231], v[234:235], 0, s[88:89]
	s_barrier
	ds_read_b128 v[180:183], v146 offset:49152
	ds_read_b128 v[184:187], v146 offset:50176
	ds_read_b128 v[188:191], v146 offset:51200
	ds_read_b128 v[192:195], v146 offset:52224
	ds_read_b128 v[196:199], v146 offset:53248
	ds_read_b128 v[200:203], v146 offset:54272
	ds_read_b128 v[206:209], v146 offset:55296
	ds_read_b128 v[210:213], v146 offset:56320
	global_load_lds_dwordx4 v[230:231], off
	v_lshl_add_u64 v[230:231], v[236:237], 0, s[88:89]
	s_mov_b32 m0, s62
	s_nop 0
	global_load_lds_dwordx4 v[230:231], off
	s_barrier
	s_waitcnt lgkmcnt(0)
	s_setprio 1
	s_waitcnt lgkmcnt(0)
	v_mfma_f32_16x16x32_bf16 v[62:65], v[148:151], v[180:183], v[62:65]
	v_mfma_f32_16x16x32_bf16 v[58:61], v[156:159], v[180:183], v[58:61]
	v_mfma_f32_16x16x32_bf16 v[54:57], v[148:151], v[188:191], v[54:57]
	v_mfma_f32_16x16x32_bf16 v[50:53], v[156:159], v[188:191], v[50:53]
	v_mfma_f32_16x16x32_bf16 v[38:41], v[148:151], v[196:199], v[38:41]
	v_mfma_f32_16x16x32_bf16 v[34:37], v[156:159], v[196:199], v[34:37]
	v_mfma_f32_16x16x32_bf16 v[22:25], v[148:151], v[206:209], v[22:25]
	v_mfma_f32_16x16x32_bf16 v[18:21], v[156:159], v[206:209], v[18:21]
	v_mfma_f32_16x16x32_bf16 v[62:65], v[152:155], v[184:187], v[62:65]
	v_mfma_f32_16x16x32_bf16 v[58:61], v[176:179], v[184:187], v[58:61]
	v_mfma_f32_16x16x32_bf16 v[54:57], v[152:155], v[192:195], v[54:57]
	v_mfma_f32_16x16x32_bf16 v[50:53], v[176:179], v[192:195], v[50:53]
	v_mfma_f32_16x16x32_bf16 v[38:41], v[152:155], v[200:203], v[38:41]
	v_mfma_f32_16x16x32_bf16 v[34:37], v[176:179], v[200:203], v[34:37]
	v_mfma_f32_16x16x32_bf16 v[22:25], v[152:155], v[210:213], v[22:25]
	v_mfma_f32_16x16x32_bf16 v[18:21], v[176:179], v[210:213], v[18:21]
	s_setprio 0
	s_barrier
	s_mov_b32 m0, vcc_hi
	v_lshl_add_u64 v[148:149], s[28:29], 0, v[0:1]
	global_load_lds_dwordx4 v[148:149], off
	v_lshl_add_u64 v[148:149], s[28:29], 0, v[134:135]
	s_mov_b32 m0, vcc_lo
	s_nop 0
	global_load_lds_dwordx4 v[148:149], off
	s_waitcnt vmcnt(6)
	s_barrier
	s_setprio 1
	v_mfma_f32_16x16x32_bf16 v[46:49], v[214:217], v[180:183], v[46:49]
	v_mfma_f32_16x16x32_bf16 v[42:45], v[222:225], v[180:183], v[42:45]
	v_mfma_f32_16x16x32_bf16 v[30:33], v[214:217], v[188:191], v[30:33]
	v_mfma_f32_16x16x32_bf16 v[26:29], v[222:225], v[188:191], v[26:29]
	v_mfma_f32_16x16x32_bf16 v[14:17], v[214:217], v[196:199], v[14:17]
	v_mfma_f32_16x16x32_bf16 v[10:13], v[222:225], v[196:199], v[10:13]
	v_mfma_f32_16x16x32_bf16 v[6:9], v[214:217], v[206:209], v[6:9]
	v_mfma_f32_16x16x32_bf16 v[2:5], v[222:225], v[206:209], v[2:5]
	v_mfma_f32_16x16x32_bf16 v[46:49], v[218:221], v[184:187], v[46:49]
	v_mfma_f32_16x16x32_bf16 v[42:45], v[226:229], v[184:187], v[42:45]
	v_mfma_f32_16x16x32_bf16 v[30:33], v[218:221], v[192:195], v[30:33]
	v_mfma_f32_16x16x32_bf16 v[26:29], v[226:229], v[192:195], v[26:29]
	v_mfma_f32_16x16x32_bf16 v[14:17], v[218:221], v[200:203], v[14:17]
	v_mfma_f32_16x16x32_bf16 v[10:13], v[226:229], v[200:203], v[10:13]
	v_mfma_f32_16x16x32_bf16 v[6:9], v[218:221], v[210:213], v[6:9]
	v_mfma_f32_16x16x32_bf16 v[2:5], v[226:229], v[210:213], v[2:5]
	s_setprio 0
	s_movk_i32 s30, 0x100
	s_andn2_b64 vcc, exec, s[26:27]
	s_mov_b64 s[28:29], -1
	s_mov_b64 s[26:27], 0
	s_barrier
	s_cbranch_vccz .LBB0_82
	v_lshl_add_u32 v148, s12, 8, v136
	v_lshl_or_b32 v150, s75, 8, v145
	v_ashrrev_i32_e32 v149, 31, v148
	v_ashrrev_i32_e32 v151, 31, v150
	v_lshlrev_b64 v[152:153], 11, v[148:149]
	v_lshl_add_u64 v[152:153], s[10:11], 0, v[152:153]
	v_lshlrev_b64 v[150:151], 1, v[150:151]
	v_lshl_add_u64 v[152:153], v[152:153], 0, v[150:151]
	s_mov_b32 s12, 0x40000
	s_mov_b64 s[14:15], 0x40000
	v_cvt_pk_bf16_f32 v62, v62, v63
	v_cvt_pk_bf16_f32 v63, v64, v65
	v_cvt_pk_bf16_f32 v64, v58, v59
	v_add_co_u32_e32 v58, vcc, s12, v152
	v_cvt_pk_bf16_f32 v70, v70, v71
	v_cvt_pk_bf16_f32 v71, v72, v73
	v_cvt_pk_bf16_f32 v72, v66, v67
	v_lshl_add_u64 v[66:67], v[152:153], 0, s[14:15]
	v_addc_co_u32_e32 v59, vcc, 0, v153, vcc
	v_cvt_pk_bf16_f32 v46, v46, v47
	v_cvt_pk_bf16_f32 v47, v48, v49
	v_cvt_pk_bf16_f32 v48, v42, v43
	v_cvt_pk_bf16_f32 v49, v44, v45
	s_mov_b32 s12, 0x48000
	v_cvt_pk_bf16_f32 v110, v110, v111
	v_cvt_pk_bf16_f32 v111, v112, v113
	v_cvt_pk_bf16_f32 v112, v106, v107
	v_or_b32_e32 v106, 16, v148
	s_cmp_lg_u64 s[6:7], 0
	s_cbranch_scc1 .Lwt_p1a
	global_store_dwordx4 v[66:67], v[46:49], off offset:256 nt
	s_branch .Lwt_p1b
.Lwt_p1a:
	global_store_dwordx4 v[66:67], v[46:49], off offset:256 sc1 nt
.Lwt_p1b:
	s_mov_b64 s[14:15], 0x48000
	v_ashrrev_i32_e32 v107, 31, v106
	v_add_co_u32_e32 v48, vcc, s12, v152
	v_cvt_pk_bf16_f32 v94, v94, v95
	v_cvt_pk_bf16_f32 v95, v96, v97
	v_cvt_pk_bf16_f32 v96, v90, v91
	v_or_b32_e32 v90, 32, v148
	v_lshl_add_u64 v[46:47], v[152:153], 0, s[14:15]
	v_addc_co_u32_e32 v49, vcc, 0, v153, vcc
	v_cvt_pk_bf16_f32 v30, v30, v31
	v_cvt_pk_bf16_f32 v31, v32, v33
	v_cvt_pk_bf16_f32 v32, v26, v27
	v_cvt_pk_bf16_f32 v33, v28, v29
	s_mov_b32 s12, 0x50000
	v_lshlrev_b64 v[106:107], 11, v[106:107]
	v_ashrrev_i32_e32 v91, 31, v90
	v_cvt_pk_bf16_f32 v78, v78, v79
	v_cvt_pk_bf16_f32 v79, v80, v81
	v_cvt_pk_bf16_f32 v80, v74, v75
	v_or_b32_e32 v74, 48, v148
	s_cmp_lg_u64 s[6:7], 0
	s_cbranch_scc1 .Lwt_p2a
	global_store_dwordx4 v[46:47], v[30:33], off offset:256 nt
	s_branch .Lwt_p2b
.Lwt_p2a:
	global_store_dwordx4 v[46:47], v[30:33], off offset:256 sc1 nt
.Lwt_p2b:
	s_mov_b64 s[14:15], 0x50000
	v_cvt_pk_bf16_f32 v113, v108, v109
	v_add_co_u32_e32 v32, vcc, s12, v152
	v_lshl_add_u64 v[106:107], s[10:11], 0, v[106:107]
	v_lshlrev_b64 v[90:91], 11, v[90:91]
	v_ashrrev_i32_e32 v75, 31, v74
	v_lshl_add_u64 v[30:31], v[152:153], 0, s[14:15]
	v_addc_co_u32_e32 v33, vcc, 0, v153, vcc
	v_cvt_pk_bf16_f32 v14, v14, v15
	v_cvt_pk_bf16_f32 v15, v16, v17
	v_cvt_pk_bf16_f32 v16, v10, v11
	v_cvt_pk_bf16_f32 v17, v12, v13
	s_mov_b32 s12, 0x58000
	s_cmp_lg_u64 s[6:7], 0
	s_cbranch_scc1 .Lwt_p3a
	global_store_dwordx4 v[152:153], v[110:113], off offset:256 nt
	s_branch .Lwt_p3b
.Lwt_p3a:
	global_store_dwordx4 v[152:153], v[110:113], off offset:256 sc1 nt
.Lwt_p3b:
	v_cvt_pk_bf16_f32 v97, v92, v93
	v_lshl_add_u64 v[90:91], s[10:11], 0, v[90:91]
	v_lshl_add_u64 v[110:111], v[106:107], 0, v[150:151]
	v_lshlrev_b64 v[74:75], 11, v[74:75]
	s_cmp_lg_u64 s[6:7], 0
	s_cbranch_scc1 .Lwt_p4a
	global_store_dwordx4 v[30:31], v[14:17], off offset:256 nt
	global_store_dwordx4 v[110:111], v[94:97], off offset:256 nt
	s_branch .Lwt_p4b
.Lwt_p4a:
	global_store_dwordx4 v[30:31], v[14:17], off offset:256 sc1 nt
	global_store_dwordx4 v[110:111], v[94:97], off offset:256 sc1 nt
.Lwt_p4b:
	v_cvt_pk_bf16_f32 v81, v76, v77
	v_add_co_u32_e32 v16, vcc, s12, v152
	v_lshl_add_u64 v[94:95], v[90:91], 0, v[150:151]
	v_lshl_add_u64 v[74:75], s[10:11], 0, v[74:75]
	s_mov_b64 s[14:15], 0x58000
	v_addc_co_u32_e32 v17, vcc, 0, v153, vcc
	v_cvt_pk_bf16_f32 v126, v126, v127
	v_cvt_pk_bf16_f32 v127, v128, v129
	v_cvt_pk_bf16_f32 v128, v122, v123
	v_cvt_pk_bf16_f32 v129, v124, v125
	v_cvt_pk_bf16_f32 v106, v118, v119
	v_cvt_pk_bf16_f32 v107, v120, v121
	v_cvt_pk_bf16_f32 v108, v114, v115
	v_cvt_pk_bf16_f32 v109, v116, v117
	v_cvt_pk_bf16_f32 v90, v102, v103
	v_cvt_pk_bf16_f32 v91, v104, v105
	v_cvt_pk_bf16_f32 v92, v98, v99
	v_cvt_pk_bf16_f32 v93, v100, v101
	s_cmp_lg_u64 s[6:7], 0
	s_cbranch_scc1 .Lwt_p5a
	global_store_dwordx4 v[94:95], v[78:81], off offset:256 nt
	s_branch .Lwt_p5b
.Lwt_p5a:
	global_store_dwordx4 v[94:95], v[78:81], off offset:256 sc1 nt
.Lwt_p5b:
	v_cvt_pk_bf16_f32 v76, v82, v83
	v_cvt_pk_bf16_f32 v77, v84, v85
	v_lshl_add_u64 v[78:79], v[74:75], 0, v[150:151]
	v_cvt_pk_bf16_f32 v74, v86, v87
	v_cvt_pk_bf16_f32 v75, v88, v89
	v_cvt_pk_bf16_f32 v73, v68, v69
	v_cvt_pk_bf16_f32 v65, v60, v61
	v_cvt_pk_bf16_f32 v42, v54, v55
	v_cvt_pk_bf16_f32 v43, v56, v57
	v_cvt_pk_bf16_f32 v44, v50, v51
	v_cvt_pk_bf16_f32 v45, v52, v53
	v_cvt_pk_bf16_f32 v26, v38, v39
	v_cvt_pk_bf16_f32 v27, v40, v41
	v_cvt_pk_bf16_f32 v28, v34, v35
	v_cvt_pk_bf16_f32 v29, v36, v37
	v_lshl_add_u64 v[14:15], v[152:153], 0, s[14:15]
	v_cvt_pk_bf16_f32 v10, v22, v23
	v_cvt_pk_bf16_f32 v11, v24, v25
	v_cvt_pk_bf16_f32 v12, v18, v19
	v_cvt_pk_bf16_f32 v13, v20, v21
	v_cvt_pk_bf16_f32 v6, v6, v7
	v_cvt_pk_bf16_f32 v7, v8, v9
	v_cvt_pk_bf16_f32 v8, v2, v3
	v_cvt_pk_bf16_f32 v9, v4, v5
	s_and_b64 vcc, exec, s[6:7]
	s_mov_b32 s75, s18
	s_mov_b32 s12, s20
	s_mov_b64 s[14:15], s[24:25]
	s_mov_b64 s[16:17], s[22:23]
	s_mov_b32 s76, 0x8000
	s_movk_i32 s77, 0x7fff
	s_cmp_lg_u64 s[6:7], 0
	s_cbranch_scc1 .Lwt_p6a
	global_store_dwordx4 v[152:153], v[126:129], off nt
	global_store_dwordx4 v[110:111], v[106:109], off nt
	global_store_dwordx4 v[94:95], v[90:93], off nt
	global_store_dwordx4 v[78:79], v[74:77], off nt
	global_store_dwordx4 v[78:79], v[70:73], off offset:256 nt
	global_store_dwordx4 v[58:59], v[62:65], off nt
	global_store_dwordx4 v[48:49], v[42:45], off nt
	global_store_dwordx4 v[32:33], v[26:29], off nt
	global_store_dwordx4 v[16:17], v[10:13], off nt
	global_store_dwordx4 v[14:15], v[6:9], off offset:256 nt
	s_branch .Lwt_p6b
.Lwt_p6a:
	global_store_dwordx4 v[152:153], v[126:129], off sc1 nt
	global_store_dwordx4 v[110:111], v[106:109], off sc1 nt
	global_store_dwordx4 v[94:95], v[90:93], off sc1 nt
	global_store_dwordx4 v[78:79], v[74:77], off sc1 nt
	global_store_dwordx4 v[78:79], v[70:73], off offset:256 sc1 nt
	global_store_dwordx4 v[58:59], v[62:65], off sc1 nt
	global_store_dwordx4 v[48:49], v[42:45], off sc1 nt
	global_store_dwordx4 v[32:33], v[26:29], off sc1 nt
	global_store_dwordx4 v[16:17], v[10:13], off sc1 nt
	global_store_dwordx4 v[14:15], v[6:9], off offset:256 sc1 nt
.Lwt_p6b:
	s_cbranch_vccz .LBB0_75
	s_waitcnt vmcnt(0)
	s_cmpk_gt_u32 s43, 0xff
	s_cbranch_scc1 .LBB0_86
	s_barrier

.LBB0_111:
	s_add_u32 s22, s20, 0xfffc0080
	s_addc_u32 s23, s21, -1
	s_add_i32 s51, 0, 0x10000
	v_add_u32_e32 v151, s51, v148
	ds_read_b128 v[152:155], v151
	ds_read_b128 v[156:159], v151 offset:1024
	ds_read_b128 v[176:179], v151 offset:2048
	ds_read_b128 v[180:183], v151 offset:3072
	s_cmp_eq_u32 s47, 12
	s_cselect_b32 s25, s15, s23
	s_cselect_b32 s24, s43, s22
	s_cselect_b32 s23, s13, s46
	s_cselect_b32 s22, s44, s45
	v_lshl_add_u64 v[218:219], s[20:21], 0, v[136:137]
	s_add_i32 m0, s11, 0xc000
	ds_read_b128 v[184:187], v150
	ds_read_b128 v[188:191], v150 offset:1024
	ds_read_b128 v[192:195], v150 offset:2048
	ds_read_b128 v[196:199], v150 offset:3072
	ds_read_b128 v[200:203], v150 offset:4096
	ds_read_b128 v[206:209], v150 offset:5120
	ds_read_b128 v[210:213], v150 offset:6144
	ds_read_b128 v[214:217], v150 offset:7168
	global_load_lds_dwordx4 v[218:219], off
	v_lshl_add_u64 v[218:219], s[20:21], 0, v[146:147]
	s_add_i32 m0, s11, 0xe000
	s_nop 0
	global_load_lds_dwordx4 v[218:219], off
	s_waitcnt lgkmcnt(8)
	s_barrier
	s_waitcnt lgkmcnt(0)
	s_setprio 1
	s_waitcnt lgkmcnt(0)
	v_mfma_f32_16x16x32_bf16 v[126:129], v[152:155], v[184:187], v[126:129]
	v_mfma_f32_16x16x32_bf16 v[122:125], v[176:179], v[184:187], v[122:125]
	v_mfma_f32_16x16x32_bf16 v[118:121], v[152:155], v[192:195], v[118:121]
	v_mfma_f32_16x16x32_bf16 v[114:117], v[176:179], v[192:195], v[114:117]
	v_mfma_f32_16x16x32_bf16 v[102:105], v[152:155], v[200:203], v[102:105]
	v_mfma_f32_16x16x32_bf16 v[98:101], v[176:179], v[200:203], v[98:101]
	v_mfma_f32_16x16x32_bf16 v[86:89], v[152:155], v[210:213], v[86:89]
	v_mfma_f32_16x16x32_bf16 v[82:85], v[176:179], v[210:213], v[82:85]
	v_mfma_f32_16x16x32_bf16 v[126:129], v[156:159], v[188:191], v[126:129]
	v_mfma_f32_16x16x32_bf16 v[122:125], v[180:183], v[188:191], v[122:125]
	v_mfma_f32_16x16x32_bf16 v[118:121], v[156:159], v[196:199], v[118:121]
	v_mfma_f32_16x16x32_bf16 v[114:117], v[180:183], v[196:199], v[114:117]
	v_mfma_f32_16x16x32_bf16 v[102:105], v[156:159], v[206:209], v[102:105]
	v_mfma_f32_16x16x32_bf16 v[98:101], v[180:183], v[206:209], v[98:101]
	v_mfma_f32_16x16x32_bf16 v[86:89], v[156:159], v[214:217], v[86:89]
	v_mfma_f32_16x16x32_bf16 v[82:85], v[180:183], v[214:217], v[82:85]
	s_setprio 0
	s_barrier
	s_add_i32 s54, 0, 0x14000
	s_add_i32 s51, s51, s34
	v_add_u32_e32 v151, s54, v148
	v_lshl_add_u64 v[234:235], s[22:23], 0, v[0:1]
	s_mov_b32 m0, s51
	ds_read_b128 v[218:221], v151
	ds_read_b128 v[222:225], v151 offset:1024
	ds_read_b128 v[226:229], v151 offset:2048
	ds_read_b128 v[230:233], v151 offset:3072
	global_load_lds_dwordx4 v[234:235], off
	v_lshl_add_u64 v[236:237], s[22:23], 0, v[134:135]
	s_add_i32 m0, s51, 0x2000
	s_nop 0
	global_load_lds_dwordx4 v[236:237], off
	s_barrier
	s_waitcnt lgkmcnt(0)
	s_setprio 1
	s_waitcnt lgkmcnt(0)
	v_mfma_f32_16x16x32_bf16 v[110:113], v[218:221], v[184:187], v[110:113]
	v_mfma_f32_16x16x32_bf16 v[106:109], v[226:229], v[184:187], v[106:109]
	v_mfma_f32_16x16x32_bf16 v[94:97], v[218:221], v[192:195], v[94:97]
	v_mfma_f32_16x16x32_bf16 v[90:93], v[226:229], v[192:195], v[90:93]
	v_mfma_f32_16x16x32_bf16 v[78:81], v[218:221], v[200:203], v[78:81]
	v_mfma_f32_16x16x32_bf16 v[74:77], v[226:229], v[200:203], v[74:77]
	v_mfma_f32_16x16x32_bf16 v[70:73], v[218:221], v[210:213], v[70:73]
	v_mfma_f32_16x16x32_bf16 v[66:69], v[226:229], v[210:213], v[66:69]
	v_mfma_f32_16x16x32_bf16 v[110:113], v[222:225], v[188:191], v[110:113]
	v_mfma_f32_16x16x32_bf16 v[106:109], v[230:233], v[188:191], v[106:109]
	v_mfma_f32_16x16x32_bf16 v[94:97], v[222:225], v[196:199], v[94:97]
	v_mfma_f32_16x16x32_bf16 v[90:93], v[230:233], v[196:199], v[90:93]
	v_mfma_f32_16x16x32_bf16 v[78:81], v[222:225], v[206:209], v[78:81]
	v_mfma_f32_16x16x32_bf16 v[74:77], v[230:233], v[206:209], v[74:77]
	v_mfma_f32_16x16x32_bf16 v[70:73], v[222:225], v[214:217], v[70:73]
	v_mfma_f32_16x16x32_bf16 v[66:69], v[230:233], v[214:217], v[66:69]
	s_setprio 0
	s_mov_b32 m0, s11
	v_lshl_add_u64 v[238:239], s[24:25], 0, v[130:131]
	s_barrier
	ds_read_b128 v[184:187], v150 offset:16384
	ds_read_b128 v[188:191], v150 offset:17408
	ds_read_b128 v[192:195], v150 offset:18432
	ds_read_b128 v[196:199], v150 offset:19456
	ds_read_b128 v[200:203], v150 offset:20480
	ds_read_b128 v[206:209], v150 offset:21504
	ds_read_b128 v[210:213], v150 offset:22528
	ds_read_b128 v[214:217], v150 offset:23552
	global_load_lds_dwordx4 v[238:239], off
	v_lshl_add_u64 v[240:241], s[24:25], 0, v[132:133]
	s_mov_b32 m0, s35
	s_nop 0
	global_load_lds_dwordx4 v[240:241], off
	s_barrier
	s_waitcnt lgkmcnt(0)
	s_setprio 1
	s_waitcnt lgkmcnt(0)
	v_mfma_f32_16x16x32_bf16 v[62:65], v[152:155], v[184:187], v[62:65]
	v_mfma_f32_16x16x32_bf16 v[58:61], v[176:179], v[184:187], v[58:61]
	v_mfma_f32_16x16x32_bf16 v[54:57], v[152:155], v[192:195], v[54:57]
	v_mfma_f32_16x16x32_bf16 v[50:53], v[176:179], v[192:195], v[50:53]
	v_mfma_f32_16x16x32_bf16 v[38:41], v[152:155], v[200:203], v[38:41]
	v_mfma_f32_16x16x32_bf16 v[34:37], v[176:179], v[200:203], v[34:37]
	v_mfma_f32_16x16x32_bf16 v[22:25], v[152:155], v[210:213], v[22:25]
	v_mfma_f32_16x16x32_bf16 v[18:21], v[176:179], v[210:213], v[18:21]
	v_mfma_f32_16x16x32_bf16 v[62:65], v[156:159], v[188:191], v[62:65]
	v_mfma_f32_16x16x32_bf16 v[58:61], v[180:183], v[188:191], v[58:61]
	v_mfma_f32_16x16x32_bf16 v[54:57], v[156:159], v[196:199], v[54:57]
	v_mfma_f32_16x16x32_bf16 v[50:53], v[180:183], v[196:199], v[50:53]
	v_mfma_f32_16x16x32_bf16 v[38:41], v[156:159], v[206:209], v[38:41]
	v_mfma_f32_16x16x32_bf16 v[34:37], v[180:183], v[206:209], v[34:37]
	v_mfma_f32_16x16x32_bf16 v[22:25], v[156:159], v[214:217], v[22:25]
	v_mfma_f32_16x16x32_bf16 v[18:21], v[180:183], v[214:217], v[18:21]
	s_setprio 0
	s_barrier
	s_add_u32 s52, s22, 0x40000
	s_addc_u32 s53, s23, 0
	s_add_i32 s51, s54, s34
	v_lshl_add_u64 v[152:153], s[52:53], 0, v[0:1]
	s_mov_b32 m0, s51
	s_nop 0
	global_load_lds_dwordx4 v[152:153], off
	v_lshl_add_u64 v[152:153], s[52:53], 0, v[134:135]
	s_add_i32 m0, s51, 0x2000
	s_nop 0
	global_load_lds_dwordx4 v[152:153], off
	s_waitcnt vmcnt(6)
	s_barrier
	s_setprio 1
	v_mfma_f32_16x16x32_bf16 v[46:49], v[218:221], v[184:187], v[46:49]
	v_mfma_f32_16x16x32_bf16 v[42:45], v[226:229], v[184:187], v[42:45]
	v_mfma_f32_16x16x32_bf16 v[30:33], v[218:221], v[192:195], v[30:33]
	v_mfma_f32_16x16x32_bf16 v[26:29], v[226:229], v[192:195], v[26:29]
	v_mfma_f32_16x16x32_bf16 v[14:17], v[218:221], v[200:203], v[14:17]
	v_mfma_f32_16x16x32_bf16 v[10:13], v[226:229], v[200:203], v[10:13]
	v_mfma_f32_16x16x32_bf16 v[6:9], v[218:221], v[210:213], v[6:9]
	v_mfma_f32_16x16x32_bf16 v[2:5], v[226:229], v[210:213], v[2:5]
	v_mfma_f32_16x16x32_bf16 v[46:49], v[222:225], v[188:191], v[46:49]
	v_mfma_f32_16x16x32_bf16 v[42:45], v[230:233], v[188:191], v[42:45]
	v_mfma_f32_16x16x32_bf16 v[30:33], v[222:225], v[196:199], v[30:33]
	v_mfma_f32_16x16x32_bf16 v[26:29], v[230:233], v[196:199], v[26:29]
	v_mfma_f32_16x16x32_bf16 v[14:17], v[222:225], v[206:209], v[14:17]
	v_mfma_f32_16x16x32_bf16 v[10:13], v[230:233], v[206:209], v[10:13]
	v_mfma_f32_16x16x32_bf16 v[6:9], v[222:225], v[214:217], v[6:9]
	v_mfma_f32_16x16x32_bf16 v[2:5], v[230:233], v[214:217], v[2:5]
	s_setprio 0
	s_add_i32 s51, 0, 0x18000
	v_add_u32_e32 v151, s51, v148
	s_barrier
	ds_read_b128 v[152:155], v151
	ds_read_b128 v[156:159], v151 offset:1024
	ds_read_b128 v[176:179], v151 offset:2048
	ds_read_b128 v[180:183], v151 offset:3072
	s_add_u32 s24, s24, 0x40000
	s_addc_u32 s25, s25, 0
	s_mov_b32 m0, s36
	v_lshl_add_u64 v[218:219], s[24:25], 0, v[130:131]
	ds_read_b128 v[184:187], v150 offset:32768
	ds_read_b128 v[188:191], v150 offset:33792
	ds_read_b128 v[192:195], v150 offset:34816
	ds_read_b128 v[196:199], v150 offset:35840
	ds_read_b128 v[200:203], v150 offset:36864
	ds_read_b128 v[206:209], v150 offset:37888
	ds_read_b128 v[210:213], v150 offset:38912
	ds_read_b128 v[214:217], v150 offset:39936
	global_load_lds_dwordx4 v[218:219], off
	v_lshl_add_u64 v[218:219], s[24:25], 0, v[132:133]
	s_mov_b32 m0, s37
	s_nop 0
	global_load_lds_dwordx4 v[218:219], off
	s_waitcnt lgkmcnt(8)
	s_barrier
	s_waitcnt lgkmcnt(0)
	s_setprio 1
	s_waitcnt lgkmcnt(0)
	v_mfma_f32_16x16x32_bf16 v[126:129], v[152:155], v[184:187], v[126:129]
	v_mfma_f32_16x16x32_bf16 v[122:125], v[176:179], v[184:187], v[122:125]
	v_mfma_f32_16x16x32_bf16 v[118:121], v[152:155], v[192:195], v[118:121]
	v_mfma_f32_16x16x32_bf16 v[114:117], v[176:179], v[192:195], v[114:117]
	v_mfma_f32_16x16x32_bf16 v[102:105], v[152:155], v[200:203], v[102:105]
	v_mfma_f32_16x16x32_bf16 v[98:101], v[176:179], v[200:203], v[98:101]
	v_mfma_f32_16x16x32_bf16 v[86:89], v[152:155], v[210:213], v[86:89]
	v_mfma_f32_16x16x32_bf16 v[82:85], v[176:179], v[210:213], v[82:85]
	v_mfma_f32_16x16x32_bf16 v[126:129], v[156:159], v[188:191], v[126:129]
	v_mfma_f32_16x16x32_bf16 v[122:125], v[180:183], v[188:191], v[122:125]
	v_mfma_f32_16x16x32_bf16 v[118:121], v[156:159], v[196:199], v[118:121]
	v_mfma_f32_16x16x32_bf16 v[114:117], v[180:183], v[196:199], v[114:117]
	v_mfma_f32_16x16x32_bf16 v[102:105], v[156:159], v[206:209], v[102:105]
	v_mfma_f32_16x16x32_bf16 v[98:101], v[180:183], v[206:209], v[98:101]
	v_mfma_f32_16x16x32_bf16 v[86:89], v[156:159], v[214:217], v[86:89]
	v_mfma_f32_16x16x32_bf16 v[82:85], v[180:183], v[214:217], v[82:85]
	s_setprio 0
	s_barrier
	s_add_i32 s24, 0, 0x1c000
	s_add_i32 s25, s51, s34
	v_add_u32_e32 v151, s24, v148
	v_lshl_add_u64 v[234:235], v[234:235], 0, s[88:89]
	s_mov_b32 m0, s25
	ds_read_b128 v[218:221], v151
	ds_read_b128 v[222:225], v151 offset:1024
	ds_read_b128 v[226:229], v151 offset:2048
	ds_read_b128 v[230:233], v151 offset:3072
	global_load_lds_dwordx4 v[234:235], off
	v_lshl_add_u64 v[234:235], v[236:237], 0, s[88:89]
	s_add_i32 m0, s25, 0x2000
	s_nop 0
	global_load_lds_dwordx4 v[234:235], off
	s_barrier
	s_waitcnt lgkmcnt(0)
	s_setprio 1
	s_waitcnt lgkmcnt(0)
	v_mfma_f32_16x16x32_bf16 v[110:113], v[218:221], v[184:187], v[110:113]
	v_mfma_f32_16x16x32_bf16 v[106:109], v[226:229], v[184:187], v[106:109]
	v_mfma_f32_16x16x32_bf16 v[94:97], v[218:221], v[192:195], v[94:97]
	v_mfma_f32_16x16x32_bf16 v[90:93], v[226:229], v[192:195], v[90:93]
	v_mfma_f32_16x16x32_bf16 v[78:81], v[218:221], v[200:203], v[78:81]
	v_mfma_f32_16x16x32_bf16 v[74:77], v[226:229], v[200:203], v[74:77]
	v_mfma_f32_16x16x32_bf16 v[70:73], v[218:221], v[210:213], v[70:73]
	v_mfma_f32_16x16x32_bf16 v[66:69], v[226:229], v[210:213], v[66:69]
	v_mfma_f32_16x16x32_bf16 v[110:113], v[222:225], v[188:191], v[110:113]
	v_mfma_f32_16x16x32_bf16 v[106:109], v[230:233], v[188:191], v[106:109]
	v_mfma_f32_16x16x32_bf16 v[94:97], v[222:225], v[196:199], v[94:97]
	v_mfma_f32_16x16x32_bf16 v[90:93], v[230:233], v[196:199], v[90:93]
	v_mfma_f32_16x16x32_bf16 v[78:81], v[222:225], v[206:209], v[78:81]
	v_mfma_f32_16x16x32_bf16 v[74:77], v[230:233], v[206:209], v[74:77]
	v_mfma_f32_16x16x32_bf16 v[70:73], v[222:225], v[214:217], v[70:73]
	v_mfma_f32_16x16x32_bf16 v[66:69], v[230:233], v[214:217], v[66:69]
	s_setprio 0
	s_mov_b32 m0, s38
	v_lshl_add_u64 v[234:235], v[238:239], 0, s[88:89]
	s_barrier
	ds_read_b128 v[184:187], v150 offset:49152
	ds_read_b128 v[188:191], v150 offset:50176
	ds_read_b128 v[192:195], v150 offset:51200
	ds_read_b128 v[196:199], v150 offset:52224
	ds_read_b128 v[200:203], v150 offset:53248
	ds_read_b128 v[206:209], v150 offset:54272
	ds_read_b128 v[210:213], v150 offset:55296
	ds_read_b128 v[214:217], v150 offset:56320
	global_load_lds_dwordx4 v[234:235], off
	v_lshl_add_u64 v[234:235], v[240:241], 0, s[88:89]
	s_mov_b32 m0, s39
	s_nop 0
	global_load_lds_dwordx4 v[234:235], off
	s_barrier
	s_waitcnt lgkmcnt(0)
	s_setprio 1
	s_waitcnt lgkmcnt(0)
	v_mfma_f32_16x16x32_bf16 v[62:65], v[152:155], v[184:187], v[62:65]
	v_mfma_f32_16x16x32_bf16 v[58:61], v[176:179], v[184:187], v[58:61]
	v_mfma_f32_16x16x32_bf16 v[54:57], v[152:155], v[192:195], v[54:57]
	v_mfma_f32_16x16x32_bf16 v[50:53], v[176:179], v[192:195], v[50:53]
	v_mfma_f32_16x16x32_bf16 v[38:41], v[152:155], v[200:203], v[38:41]
	v_mfma_f32_16x16x32_bf16 v[34:37], v[176:179], v[200:203], v[34:37]
	v_mfma_f32_16x16x32_bf16 v[22:25], v[152:155], v[210:213], v[22:25]
	v_mfma_f32_16x16x32_bf16 v[18:21], v[176:179], v[210:213], v[18:21]
	v_mfma_f32_16x16x32_bf16 v[62:65], v[156:159], v[188:191], v[62:65]
	v_mfma_f32_16x16x32_bf16 v[58:61], v[180:183], v[188:191], v[58:61]
	v_mfma_f32_16x16x32_bf16 v[54:57], v[156:159], v[196:199], v[54:57]
	v_mfma_f32_16x16x32_bf16 v[50:53], v[180:183], v[196:199], v[50:53]
	v_mfma_f32_16x16x32_bf16 v[38:41], v[156:159], v[206:209], v[38:41]
	v_mfma_f32_16x16x32_bf16 v[34:37], v[180:183], v[206:209], v[34:37]
	v_mfma_f32_16x16x32_bf16 v[22:25], v[156:159], v[214:217], v[22:25]
	v_mfma_f32_16x16x32_bf16 v[18:21], v[180:183], v[214:217], v[18:21]
	s_setprio 0
	s_barrier
	s_add_u32 s22, s22, 0x40080
	s_addc_u32 s23, s23, 0
	s_add_i32 s24, s24, s34
	v_lshl_add_u64 v[152:153], s[22:23], 0, v[0:1]
	s_mov_b32 m0, s24
	s_nop 0
	global_load_lds_dwordx4 v[152:153], off
	v_lshl_add_u64 v[152:153], s[22:23], 0, v[134:135]
	s_add_i32 m0, s24, 0x2000
	s_nop 0
	global_load_lds_dwordx4 v[152:153], off
	s_waitcnt vmcnt(6)
	s_barrier
	s_setprio 1
	v_mfma_f32_16x16x32_bf16 v[46:49], v[218:221], v[184:187], v[46:49]
	v_mfma_f32_16x16x32_bf16 v[42:45], v[226:229], v[184:187], v[42:45]
	v_mfma_f32_16x16x32_bf16 v[30:33], v[218:221], v[192:195], v[30:33]
	v_mfma_f32_16x16x32_bf16 v[26:29], v[226:229], v[192:195], v[26:29]
	v_mfma_f32_16x16x32_bf16 v[14:17], v[218:221], v[200:203], v[14:17]
	v_mfma_f32_16x16x32_bf16 v[10:13], v[226:229], v[200:203], v[10:13]
	v_mfma_f32_16x16x32_bf16 v[6:9], v[218:221], v[210:213], v[6:9]
	v_mfma_f32_16x16x32_bf16 v[2:5], v[226:229], v[210:213], v[2:5]
	v_mfma_f32_16x16x32_bf16 v[46:49], v[222:225], v[188:191], v[46:49]
	v_mfma_f32_16x16x32_bf16 v[42:45], v[230:233], v[188:191], v[42:45]
	v_mfma_f32_16x16x32_bf16 v[30:33], v[222:225], v[196:199], v[30:33]
	v_mfma_f32_16x16x32_bf16 v[26:29], v[230:233], v[196:199], v[26:29]
	v_mfma_f32_16x16x32_bf16 v[14:17], v[222:225], v[206:209], v[14:17]
	v_mfma_f32_16x16x32_bf16 v[10:13], v[230:233], v[206:209], v[10:13]
	v_mfma_f32_16x16x32_bf16 v[6:9], v[222:225], v[214:217], v[6:9]
	v_mfma_f32_16x16x32_bf16 v[2:5], v[230:233], v[214:217], v[2:5]
	s_setprio 0
	s_add_i32 s47, s47, 2
	s_add_u32 s20, s20, 0x100
	s_addc_u32 s21, s21, 0
	s_add_u32 s45, s45, 0x100
	s_addc_u32 s46, s46, 0
	s_cmp_gt_u32 s47, 13
	s_barrier
	s_cbranch_scc0 .LBB0_111
	v_lshl_add_u32 v152, s10, 8, v145
	v_lshl_or_b32 v154, s41, 8, v149
	v_ashrrev_i32_e32 v153, 31, v152
	v_ashrrev_i32_e32 v155, 31, v154
	v_lshlrev_b64 v[156:157], 11, v[152:153]
	v_lshl_add_u64 v[156:157], s[8:9], 0, v[156:157]
	v_lshlrev_b64 v[154:155], 1, v[154:155]
	v_lshl_add_u64 v[156:157], v[156:157], 0, v[154:155]
	s_mov_b32 s10, 0x40000
	s_mov_b64 s[20:21], 0x40000
	v_cvt_pk_bf16_f32 v62, v62, v63
	v_cvt_pk_bf16_f32 v63, v64, v65
	v_cvt_pk_bf16_f32 v64, v58, v59
	v_add_co_u32_e32 v58, vcc, s10, v156
	v_cvt_pk_bf16_f32 v70, v70, v71
	v_cvt_pk_bf16_f32 v71, v72, v73
	v_cvt_pk_bf16_f32 v72, v66, v67
	v_lshl_add_u64 v[66:67], v[156:157], 0, s[20:21]
	v_addc_co_u32_e32 v59, vcc, 0, v157, vcc
	v_cvt_pk_bf16_f32 v46, v46, v47
	v_cvt_pk_bf16_f32 v47, v48, v49
	v_cvt_pk_bf16_f32 v48, v42, v43
	v_cvt_pk_bf16_f32 v49, v44, v45
	s_mov_b32 s10, 0x48000
	v_cvt_pk_bf16_f32 v110, v110, v111
	v_cvt_pk_bf16_f32 v111, v112, v113
	v_cvt_pk_bf16_f32 v112, v106, v107
	v_or_b32_e32 v106, 16, v152
	s_cmp_lg_u64 s[6:7], 0
	s_cbranch_scc1 .Lwt_q1a
	global_store_dwordx4 v[66:67], v[46:49], off offset:256 nt
	s_branch .Lwt_q1b

.Lwt_q1b:
	s_mov_b64 s[20:21], 0x48000
	v_ashrrev_i32_e32 v107, 31, v106
	v_add_co_u32_e32 v48, vcc, s10, v156
	v_cvt_pk_bf16_f32 v94, v94, v95
	v_cvt_pk_bf16_f32 v95, v96, v97
	v_cvt_pk_bf16_f32 v96, v90, v91
	v_or_b32_e32 v90, 32, v152
	v_lshl_add_u64 v[46:47], v[156:157], 0, s[20:21]
	v_addc_co_u32_e32 v49, vcc, 0, v157, vcc
	v_cvt_pk_bf16_f32 v30, v30, v31
	v_cvt_pk_bf16_f32 v31, v32, v33
	v_cvt_pk_bf16_f32 v32, v26, v27
	v_cvt_pk_bf16_f32 v33, v28, v29
	s_mov_b32 s10, 0x50000
	v_lshlrev_b64 v[106:107], 11, v[106:107]
	v_ashrrev_i32_e32 v91, 31, v90
	v_cvt_pk_bf16_f32 v78, v78, v79
	v_cvt_pk_bf16_f32 v79, v80, v81
	v_cvt_pk_bf16_f32 v80, v74, v75
	v_or_b32_e32 v74, 48, v152
	s_cmp_lg_u64 s[6:7], 0
	s_cbranch_scc1 .Lwt_q2a
	global_store_dwordx4 v[46:47], v[30:33], off offset:256 nt
	s_branch .Lwt_q2b

.Lwt_q2b:
	s_mov_b64 s[20:21], 0x50000
	v_cvt_pk_bf16_f32 v113, v108, v109
	v_add_co_u32_e32 v32, vcc, s10, v156
	v_lshl_add_u64 v[106:107], s[8:9], 0, v[106:107]
	v_lshlrev_b64 v[90:91], 11, v[90:91]
	v_ashrrev_i32_e32 v75, 31, v74
	v_lshl_add_u64 v[30:31], v[156:157], 0, s[20:21]
	v_addc_co_u32_e32 v33, vcc, 0, v157, vcc
	v_cvt_pk_bf16_f32 v14, v14, v15
	v_cvt_pk_bf16_f32 v15, v16, v17
	v_cvt_pk_bf16_f32 v16, v10, v11
	v_cvt_pk_bf16_f32 v17, v12, v13
	s_mov_b32 s10, 0x58000
	s_cmp_lg_u64 s[6:7], 0
	s_cbranch_scc1 .Lwt_q3a
	global_store_dwordx4 v[156:157], v[110:113], off offset:256 nt
	s_branch .Lwt_q3b
.Lwt_q3a:
	global_store_dwordx4 v[156:157], v[110:113], off offset:256 sc1 nt
.Lwt_q3b:
	v_cvt_pk_bf16_f32 v97, v92, v93
	v_lshl_add_u64 v[90:91], s[8:9], 0, v[90:91]
	v_lshl_add_u64 v[110:111], v[106:107], 0, v[154:155]
	v_lshlrev_b64 v[74:75], 11, v[74:75]
	s_cmp_lg_u64 s[6:7], 0
	s_cbranch_scc1 .Lwt_q4a
	global_store_dwordx4 v[30:31], v[14:17], off offset:256 nt
	global_store_dwordx4 v[110:111], v[94:97], off offset:256 nt
	s_branch .Lwt_q4b

.Lwt_q4b:
	v_cvt_pk_bf16_f32 v81, v76, v77
	v_add_co_u32_e32 v16, vcc, s10, v156
	v_lshl_add_u64 v[94:95], v[90:91], 0, v[154:155]
	v_lshl_add_u64 v[74:75], s[8:9], 0, v[74:75]
	s_mov_b64 s[20:21], 0x58000
	v_addc_co_u32_e32 v17, vcc, 0, v157, vcc
	v_cvt_pk_bf16_f32 v126, v126, v127
	v_cvt_pk_bf16_f32 v127, v128, v129
	v_cvt_pk_bf16_f32 v128, v122, v123
	v_cvt_pk_bf16_f32 v129, v124, v125
	v_cvt_pk_bf16_f32 v106, v118, v119
	v_cvt_pk_bf16_f32 v107, v120, v121
	v_cvt_pk_bf16_f32 v108, v114, v115
	v_cvt_pk_bf16_f32 v109, v116, v117
	v_cvt_pk_bf16_f32 v90, v102, v103
	v_cvt_pk_bf16_f32 v91, v104, v105
	v_cvt_pk_bf16_f32 v92, v98, v99
	v_cvt_pk_bf16_f32 v93, v100, v101
	s_cmp_lg_u64 s[6:7], 0
	s_cbranch_scc1 .Lwt_q5a
	global_store_dwordx4 v[94:95], v[78:81], off offset:256 nt
	s_branch .Lwt_q5b

.Lwt_q5b:
	v_cvt_pk_bf16_f32 v76, v82, v83
	v_cvt_pk_bf16_f32 v77, v84, v85
	v_lshl_add_u64 v[78:79], v[74:75], 0, v[154:155]
	v_cvt_pk_bf16_f32 v74, v86, v87
	v_cvt_pk_bf16_f32 v75, v88, v89
	v_cvt_pk_bf16_f32 v73, v68, v69
	v_cvt_pk_bf16_f32 v65, v60, v61
	v_cvt_pk_bf16_f32 v42, v54, v55
	v_cvt_pk_bf16_f32 v43, v56, v57
	v_cvt_pk_bf16_f32 v44, v50, v51
	v_cvt_pk_bf16_f32 v45, v52, v53
	v_cvt_pk_bf16_f32 v26, v38, v39
	v_cvt_pk_bf16_f32 v27, v40, v41
	v_cvt_pk_bf16_f32 v28, v34, v35
	v_cvt_pk_bf16_f32 v29, v36, v37
	v_lshl_add_u64 v[14:15], v[156:157], 0, s[20:21]
	v_cvt_pk_bf16_f32 v10, v22, v23
	v_cvt_pk_bf16_f32 v11, v24, v25
	v_cvt_pk_bf16_f32 v12, v18, v19
	v_cvt_pk_bf16_f32 v13, v20, v21
	v_cvt_pk_bf16_f32 v6, v6, v7
	v_cvt_pk_bf16_f32 v7, v8, v9
	v_cvt_pk_bf16_f32 v8, v2, v3
	v_cvt_pk_bf16_f32 v9, v4, v5
	s_and_b64 vcc, exec, s[6:7]
	s_mov_b32 s41, s12
	s_mov_b32 s10, s14
	s_mov_b64 s[22:23], s[18:19]
	s_mov_b64 s[20:21], s[16:17]
	s_cmp_lg_u64 s[6:7], 0
	s_cbranch_scc1 .Lwt_q6a
	global_store_dwordx4 v[156:157], v[126:129], off nt
	global_store_dwordx4 v[110:111], v[106:109], off nt
	global_store_dwordx4 v[94:95], v[90:93], off nt
	global_store_dwordx4 v[78:79], v[74:77], off nt
	global_store_dwordx4 v[78:79], v[70:73], off offset:256 nt
	global_store_dwordx4 v[58:59], v[62:65], off nt
	global_store_dwordx4 v[48:49], v[42:45], off nt
	global_store_dwordx4 v[32:33], v[26:29], off nt
	global_store_dwordx4 v[16:17], v[10:13], off nt
	global_store_dwordx4 v[14:15], v[6:9], off offset:256 nt
	s_branch .Lwt_q6b
.Lwt_q6a:
	global_store_dwordx4 v[156:157], v[126:129], off sc1 nt
	global_store_dwordx4 v[110:111], v[106:109], off sc1 nt
	global_store_dwordx4 v[94:95], v[90:93], off sc1 nt
	global_store_dwordx4 v[78:79], v[74:77], off sc1 nt
	global_store_dwordx4 v[78:79], v[70:73], off offset:256 sc1 nt
	global_store_dwordx4 v[58:59], v[62:65], off sc1 nt
	global_store_dwordx4 v[48:49], v[42:45], off sc1 nt
	global_store_dwordx4 v[32:33], v[26:29], off sc1 nt
	global_store_dwordx4 v[16:17], v[10:13], off sc1 nt
	global_store_dwordx4 v[14:15], v[6:9], off offset:256 sc1 nt
.Lwt_q6b:
	s_cbranch_vccz .LBB0_104
	s_waitcnt vmcnt(0)
	s_cmpk_gt_u32 s26, 0xff
	s_cbranch_scc1 .LBB0_115
	s_barrier
